# attention k-loop PV second key-half: all 8 V fragments (16 ds_read_b64) prefetched into spare VGPRs, 16 MFMAs behind counted lgkmcnt (was read-wait(0)-2mfma x8)
# speedup vs baseline: 1.0020x; 1.0020x over previous
.LBB0_720:
	s_or_b64 exec, exec, s[10:11]
	s_and_b32 s13, 1, s12
	s_cselect_b32 s10, 0, 0x8c00
	s_add_i32 s10, s10, 16
	v_add3_u32 v114, s10, v158, v105
	ds_read_b128 v[118:121], v114
	ds_read_b128 v[122:125], v114 offset:64
	ds_read_b128 v[126:129], v114 offset:4352
	ds_read_b128 v[130:133], v114 offset:4416
	s_waitcnt lgkmcnt(3)
	v_mfma_f32_16x16x32_bf16 v[118:121], v[118:121], v[36:39], 0
	s_waitcnt lgkmcnt(1)
	v_mfma_f32_16x16x32_bf16 v[126:129], v[126:129], v[36:39], 0
	s_nop 0
	v_mfma_f32_16x16x32_bf16 v[118:121], v[122:125], v[40:43], v[118:121]
	ds_read_b128 v[122:125], v114 offset:8704
	s_waitcnt lgkmcnt(1)
	v_mfma_f32_16x16x32_bf16 v[126:129], v[130:133], v[40:43], v[126:129]
	ds_read_b128 v[130:133], v114 offset:8768
	ds_read_b128 v[138:141], v114 offset:13056
	ds_read_b128 v[160:163], v114 offset:13120
	s_waitcnt lgkmcnt(3)
	v_mfma_f32_16x16x32_bf16 v[122:125], v[122:125], v[36:39], 0
	s_waitcnt lgkmcnt(2)
	v_mfma_f32_16x16x32_bf16 v[130:133], v[130:133], v[40:43], v[122:125]
	s_nop 5
	v_max3_f32 v122, v118, s26, v119
	v_max3_f32 v122, v122, v120, v121
	v_max3_f32 v134, v122, v126, v127
	s_waitcnt lgkmcnt(1)
	v_mfma_f32_16x16x32_bf16 v[122:125], v[138:141], v[36:39], 0
	v_max3_f32 v134, v134, v128, v129
	v_max3_f32 v134, v134, v130, v131
	v_max3_f32 v134, v134, v132, v133
	s_waitcnt lgkmcnt(0)
	v_mfma_f32_16x16x32_bf16 v[138:141], v[160:163], v[40:43], v[122:125]
	s_nop 7
	v_max3_f32 v122, v134, v138, v139
	v_max3_f32 v122, v122, v140, v141
	v_mul_f32_e32 v134, 0x3e38aa3b, v122
	v_mul_f32_e32 v135, 0x3e38aa3b, v122
	ds_read_b128 v[122:125], v114 offset:128
	ds_read_b128 v[166:169], v114 offset:192
	ds_read_b128 v[170:173], v114 offset:4544
	s_nop 0
	v_permlane16_swap_b32_e32 v134, v135
	v_max_f32_e32 v134, v134, v135
	v_mov_b32_e32 v135, v134
	s_nop 1
	v_permlane32_swap_b32_e32 v134, v135
	s_waitcnt lgkmcnt(2)
	v_mfma_f32_16x16x32_bf16 v[122:125], v[122:125], v[48:51], 0
	v_max3_f32 v159, v117, v134, v135
	v_sub_f32_e32 v134, v117, v159
	v_fma_f32 v117, v118, s27, -v159
	v_fma_f32 v118, v119, s27, -v159
	v_fma_f32 v119, v120, s27, -v159
	v_fma_f32 v120, v121, s27, -v159
	v_exp_f32_e32 v162, v118
	v_exp_f32_e32 v163, v119
	v_exp_f32_e32 v164, v120
	ds_read_b128 v[118:121], v114 offset:4480
	s_waitcnt lgkmcnt(2)
	v_mfma_f32_16x16x32_bf16 v[174:177], v[166:169], v[52:55], v[122:125]
	v_exp_f32_e32 v161, v117
	v_fma_f32 v117, v126, s27, -v159
	v_exp_f32_e32 v165, v117
	ds_read_b128 v[122:125], v114 offset:8832
	s_waitcnt lgkmcnt(1)
	v_mfma_f32_16x16x32_bf16 v[118:121], v[118:121], v[48:51], 0
	v_fma_f32 v117, v127, s27, -v159
	v_exp_f32_e32 v166, v117
	v_fma_f32 v117, v128, s27, -v159
	v_fma_f32 v135, v129, s27, -v159
	ds_read_b128 v[126:129], v114 offset:8896
	v_mfma_f32_16x16x32_bf16 v[178:181], v[170:173], v[52:55], v[118:121]
	ds_read_b128 v[168:171], v114 offset:13184
	ds_read_b128 v[182:185], v114 offset:13248
	v_fma_f32 v114, v132, s27, -v159
	s_waitcnt lgkmcnt(3)
	v_mfma_f32_16x16x32_bf16 v[122:125], v[122:125], v[48:51], 0
	v_fma_f32 v118, v130, s27, -v159
	v_exp_f32_e32 v121, v118
	v_fma_f32 v118, v131, s27, -v159
	s_waitcnt lgkmcnt(2)
	v_mfma_f32_16x16x32_bf16 v[186:189], v[126:129], v[52:55], v[122:125]
	v_exp_f32_e32 v119, v135
	v_exp_f32_e32 v136, v134
	v_exp_f32_e32 v117, v117
	s_waitcnt lgkmcnt(1)
	v_mfma_f32_16x16x32_bf16 v[128:131], v[168:171], v[48:51], 0
	v_exp_f32_e32 v123, v118
	v_max3_f32 v118, v174, s26, v175
	v_max3_f32 v118, v118, v176, v177
	s_waitcnt lgkmcnt(0)
	v_mfma_f32_16x16x32_bf16 v[182:185], v[182:185], v[52:55], v[128:131]
	v_max3_f32 v118, v118, v178, v179
	v_max3_f32 v118, v118, v180, v181
	v_max3_f32 v118, v118, v186, v187
	v_max3_f32 v118, v118, v188, v189
	v_exp_f32_e32 v125, v114
	s_nop 2
	v_max3_f32 v118, v118, v182, v183
	v_max3_f32 v118, v118, v184, v185
	v_mul_f32_e32 v118, 0x3e38aa3b, v118
	v_fma_f32 v114, v133, s27, -v159
	v_mov_b32_e32 v120, v118
	v_exp_f32_e32 v127, v114
	v_fma_f32 v114, v138, s27, -v159
	v_permlane16_swap_b32_e32 v118, v120
	v_exp_f32_e32 v129, v114
	v_max_f32_e32 v118, v118, v120
	v_fma_f32 v114, v139, s27, -v159
	v_mov_b32_e32 v120, v118
	v_exp_f32_e32 v131, v114
	v_fma_f32 v114, v140, s27, -v159
	v_permlane32_swap_b32_e32 v118, v120
	v_exp_f32_e32 v133, v114
	v_fma_f32 v114, v141, s27, -v159
	v_max3_f32 v160, v116, v118, v120
	v_exp_f32_e32 v135, v114
	v_sub_f32_e32 v114, v116, v160
	v_fma_f32 v116, v174, s27, -v160
	v_exp_f32_e32 v167, v116
	v_fma_f32 v116, v175, s27, -v160
	v_exp_f32_e32 v168, v116
	v_fma_f32 v116, v176, s27, -v160
	v_exp_f32_e32 v169, v116
	v_fma_f32 v116, v177, s27, -v160
	v_exp_f32_e32 v138, v114
	v_lshlrev_b32_e32 v114, 1, v3
	v_exp_f32_e32 v170, v116
	v_fma_f32 v116, v178, s27, -v160
	v_add3_u32 v139, s10, v115, v114
	v_add3_u32 v178, s10, v152, v114
	v_add_u32_e32 v173, 0x4000, v139
	v_add_u32_e32 v190, 0x4000, v178
	v_fma_f32 v128, v182, s27, -v160
	v_fma_f32 v130, v183, s27, -v160
	v_fma_f32 v132, v184, s27, -v160
	v_fma_f32 v134, v185, s27, -v160
	ds_read_b64 v[174:175], v173 offset:1024
	ds_read_b64 v[176:177], v173 offset:1056
	ds_read_b64 v[182:183], v190 offset:1024
	ds_read_b64 v[184:185], v190 offset:1056
	v_exp_f32_e32 v171, v116
	v_fma_f32 v116, v179, s27, -v160
	v_exp_f32_e32 v172, v116
	v_fma_f32 v116, v180, s27, -v160
	v_fma_f32 v118, v181, s27, -v160
	v_exp_f32_e32 v116, v116
	v_exp_f32_e32 v118, v118
	v_pk_mul_f32 v[98:99], v[98:99], v[136:137] op_sel_hi:[1,0]
	v_pk_mul_f32 v[96:97], v[96:97], v[136:137] op_sel_hi:[1,0]
	v_pk_mul_f32 v[94:95], v[94:95], v[136:137] op_sel_hi:[1,0]
	v_pk_mul_f32 v[92:93], v[92:93], v[136:137] op_sel_hi:[1,0]
	v_cvt_pk_bf16_f32 v143, v117, v119
	v_cvt_pk_bf16_f32 v142, v165, v166
	v_cvt_pk_bf16_f32 v141, v163, v164
	v_cvt_pk_bf16_f32 v140, v161, v162
	v_pk_mul_f32 v[82:83], v[82:83], v[138:139] op_sel_hi:[1,0]
	v_pk_mul_f32 v[80:81], v[80:81], v[138:139] op_sel_hi:[1,0]
	v_cvt_pk_bf16_f32 v181, v116, v118
	v_cvt_pk_bf16_f32 v180, v171, v172
	v_cvt_pk_bf16_f32 v179, v169, v170
	v_cvt_pk_bf16_f32 v178, v167, v168
	v_pk_mul_f32 v[70:71], v[70:71], v[138:139] op_sel_hi:[1,0]
	v_pk_mul_f32 v[68:69], v[68:69], v[138:139] op_sel_hi:[1,0]
	s_waitcnt lgkmcnt(2)
	v_mfma_f32_16x16x32_bf16 v[96:99], v[174:177], v[140:143], v[96:99]
	v_mul_f32_e64 v78, v78, v136
	v_mul_f32_e64 v79, v79, v136
	v_pk_mul_f32 v[76:77], v[76:77], v[136:137] op_sel_hi:[1,0]
	v_pk_mul_f32 v[74:75], v[74:75], v[136:137] op_sel_hi:[1,0]
	v_mfma_f32_16x16x32_bf16 v[80:83], v[174:177], v[178:181], v[80:83]
	v_add3_u32 v174, s10, v153, v114
	v_add_u32_e32 v191, 0x4000, v174
	ds_read_b64 v[174:175], v191 offset:1024
	ds_read_b64 v[176:177], v191 offset:1056
	s_waitcnt lgkmcnt(2)
	v_mfma_f32_16x16x32_bf16 v[92:95], v[182:185], v[140:143], v[92:95]
	v_mul_f32_e64 v58, v58, v138
	v_mul_f32_e64 v59, v59, v138
	v_pk_mul_f32 v[56:57], v[56:57], v[138:139] op_sel_hi:[1,0]
	v_pk_mul_f32 v[72:73], v[72:73], v[136:137] op_sel_hi:[1,0]
	v_mfma_f32_16x16x32_bf16 v[68:71], v[182:185], v[178:181], v[68:71]
	v_add3_u32 v182, s10, v154, v114
	v_add_u32_e32 v192, 0x4000, v182
	ds_read_b64 v[182:183], v192 offset:1024
	ds_read_b64 v[184:185], v192 offset:1056
	v_add_u32_e32 v193, 0x6800, v139
	v_pk_mul_f32 v[26:27], v[26:27], v[138:139] op_sel_hi:[1,0]
	v_pk_mul_f32 v[24:25], v[24:25], v[138:139] op_sel_hi:[1,0]
	v_add_u32_e32 v194, 0x7000, v139
	s_waitcnt lgkmcnt(2)
	v_mfma_f32_16x16x32_bf16 v[76:79], v[174:177], v[140:143], v[76:79]
	v_mul_f32_e64 v62, v62, v136
	v_mul_f32_e64 v63, v63, v136
	v_pk_mul_f32 v[60:61], v[60:61], v[136:137] op_sel_hi:[1,0]
	v_pk_mul_f32 v[30:31], v[30:31], v[136:137] op_sel_hi:[1,0]
	v_mfma_f32_16x16x32_bf16 v[56:59], v[174:177], v[178:181], v[56:59]
	ds_read_b64 v[174:175], v193
	ds_read_b64 v[176:177], v193 offset:32
	v_pk_mul_f32 v[66:67], v[66:67], v[138:139] op_sel_hi:[1,0]
	v_pk_mul_f32 v[64:65], v[64:65], v[138:139] op_sel_hi:[1,0]
	s_waitcnt lgkmcnt(2)
	v_mfma_f32_16x16x32_bf16 v[72:75], v[182:185], v[140:143], v[72:75]
	v_mul_f32_e64 v28, v28, v136
	v_mul_f32_e64 v29, v29, v136
	v_add_u32_e32 v195, 0x7800, v139
	v_pk_mul_f32 v[46:47], v[46:47], v[138:139] op_sel_hi:[1,0]
	v_mfma_f32_16x16x32_bf16 v[24:27], v[182:185], v[178:181], v[24:27]
	ds_read_b64 v[182:183], v194 offset:256
	ds_read_b64 v[184:185], v194 offset:288
	v_pk_mul_f32 v[44:45], v[44:45], v[138:139] op_sel_hi:[1,0]
	v_add_u32_e32 v139, 0x8000, v139
	s_waitcnt lgkmcnt(2)
	v_mfma_f32_16x16x32_bf16 v[60:63], v[174:177], v[140:143], v[60:63]
	v_mul_f32_e64 v34, v34, v138
	v_mul_f32_e64 v35, v35, v138
	v_pk_mul_f32 v[32:33], v[32:33], v[138:139] op_sel_hi:[1,0]
	v_pk_mul_f32 v[90:91], v[90:91], v[138:139] op_sel_hi:[1,0]
	v_mfma_f32_16x16x32_bf16 v[64:67], v[174:177], v[178:181], v[64:67]
	ds_read_b64 v[174:175], v195 offset:512
	ds_read_b64 v[176:177], v195 offset:544
	v_pk_mul_f32 v[88:89], v[88:89], v[138:139] op_sel_hi:[1,0]
	v_fma_f32 v120, v186, s27, -v160
	s_waitcnt lgkmcnt(2)
	v_mfma_f32_16x16x32_bf16 v[28:31], v[182:185], v[140:143], v[28:31]
	v_fma_f32 v122, v187, s27, -v160
	v_fma_f32 v124, v188, s27, -v160
	v_fma_f32 v126, v189, s27, -v160
	v_mfma_f32_16x16x32_bf16 v[44:47], v[182:185], v[178:181], v[44:47]
	ds_read_b64 v[182:183], v139 offset:768
	ds_read_b64 v[184:185], v139 offset:800
	ds_read_b64 v[196:197], v190 offset:1088
	ds_read_b64 v[198:199], v190 offset:1120
	ds_read_b64 v[200:201], v173 offset:1088
	ds_read_b64 v[202:203], v173 offset:1120
	ds_read_b64 v[204:205], v191 offset:1088
	ds_read_b64 v[206:207], v191 offset:1120
	ds_read_b64 v[208:209], v192 offset:1088
	ds_read_b64 v[210:211], v192 offset:1120
	ds_read_b64 v[212:213], v193 offset:64
	ds_read_b64 v[214:215], v193 offset:96
	ds_read_b64 v[216:217], v194 offset:320
	ds_read_b64 v[218:219], v194 offset:352
	ds_read_b64 v[220:221], v195 offset:576
	ds_read_b64 v[222:223], v195 offset:608
	ds_read_b64 v[226:227], v139 offset:832
	ds_read_b64 v[228:229], v139 offset:864
	v_exp_f32_e32 v120, v120
	v_exp_f32_e32 v122, v122
	s_waitcnt lgkmcnt(15)
	v_mfma_f32_16x16x32_bf16 v[32:35], v[174:177], v[178:181], v[32:35]
	v_exp_f32_e32 v124, v124
	v_exp_f32_e32 v126, v126
	v_exp_f32_e32 v128, v128
	s_waitcnt lgkmcnt(15)
	v_mfma_f32_16x16x32_bf16 v[88:91], v[182:185], v[178:181], v[88:91]
	v_exp_f32_e32 v130, v130
	v_exp_f32_e32 v132, v132
	v_exp_f32_e32 v134, v134
	v_pk_mul_f32 v[22:23], v[22:23], v[136:137] op_sel_hi:[1,0]
	v_pk_mul_f32 v[20:21], v[20:21], v[136:137] op_sel_hi:[1,0]
	v_pk_mul_f32 v[86:87], v[86:87], v[136:137] op_sel_hi:[1,0]
	v_pk_mul_f32 v[84:85], v[84:85], v[136:137] op_sel_hi:[1,0]
	v_mfma_f32_16x16x32_bf16 v[20:23], v[174:177], v[140:143], v[20:23]
	v_cvt_pk_bf16_f32 v177, v133, v135
	v_cvt_pk_bf16_f32 v176, v129, v131
	v_cvt_pk_bf16_f32 v175, v125, v127
	v_mfma_f32_16x16x32_bf16 v[84:87], v[182:185], v[140:143], v[84:87]
	v_cvt_pk_bf16_f32 v174, v121, v123
	v_cvt_pk_bf16_f32 v143, v132, v134
	v_cvt_pk_bf16_f32 v142, v128, v130
	v_cvt_pk_bf16_f32 v141, v124, v126
	v_cvt_pk_bf16_f32 v140, v120, v122
	s_waitcnt lgkmcnt(14)
	v_mfma_f32_16x16x32_bf16 v[92:95], v[196:199], v[174:177], v[92:95]
	v_mfma_f32_16x16x32_bf16 v[68:71], v[196:199], v[140:143], v[68:71]
	s_waitcnt lgkmcnt(10)
	v_mfma_f32_16x16x32_bf16 v[76:79], v[204:207], v[174:177], v[76:79]
	v_mfma_f32_16x16x32_bf16 v[56:59], v[204:207], v[140:143], v[56:59]
	s_waitcnt lgkmcnt(8)
	v_mfma_f32_16x16x32_bf16 v[72:75], v[208:211], v[174:177], v[72:75]
	v_mfma_f32_16x16x32_bf16 v[24:27], v[208:211], v[140:143], v[24:27]
	s_waitcnt lgkmcnt(6)
	v_mfma_f32_16x16x32_bf16 v[60:63], v[212:215], v[174:177], v[60:63]
	v_mfma_f32_16x16x32_bf16 v[64:67], v[212:215], v[140:143], v[64:67]
	s_waitcnt lgkmcnt(4)
	v_mfma_f32_16x16x32_bf16 v[28:31], v[216:219], v[174:177], v[28:31]
	v_mfma_f32_16x16x32_bf16 v[44:47], v[216:219], v[140:143], v[44:47]
	s_waitcnt lgkmcnt(2)
	v_mfma_f32_16x16x32_bf16 v[20:23], v[220:223], v[174:177], v[20:23]
	v_mfma_f32_16x16x32_bf16 v[32:35], v[220:223], v[140:143], v[32:35]
	v_mfma_f32_16x16x32_bf16 v[96:99], v[200:203], v[174:177], v[96:99]
	v_mfma_f32_16x16x32_bf16 v[80:83], v[200:203], v[140:143], v[80:83]
	s_waitcnt lgkmcnt(0)
	v_mfma_f32_16x16x32_bf16 v[84:87], v[226:229], v[174:177], v[84:87]
	v_mfma_f32_16x16x32_bf16 v[88:91], v[226:229], v[140:143], v[88:91]
	s_and_saveexec_b64 s[10:11], s[6:7]
	s_cbranch_execz .LBB0_717
	s_cmp_eq_u32 s13, 1
	s_cselect_b32 s6, 0x8c00, 0
	s_add_i32 s6, s6, 16
	v_add3_u32 v139, s6, v155, v102
	s_waitcnt vmcnt(0)
	ds_write_b128 v139, v[4:7]
	ds_write_b128 v139, v[8:11] offset:8704
	v_add3_u32 v139, s6, v156, v104
	ds_write_b128 v139, v[12:15] offset:17408
	ds_write_b128 v139, v[16:19] offset:26624
	s_branch .LBB0_717
